# grid barrier (all but the first): designated XCD leader + counter polling (no returning atomics, no TOPGEN hop); leader = the one elected by the first barrier
# speedup vs baseline: 1.0047x; 1.0047x over previous
; DI unsigned char* wsp() { return (unsigned char*)inp(25); }
; #define LAS __attribute__((address_space(3)))
; #define G_WS (wsp())
; __global__ void __launch_bounds__(512, 2) mega(Params p) {
;   cg::grid_group grid = cg::this_grid();
;   const int nb = gridDim.x, bid = blockIdx.x, t = threadIdx.x;
;   if (wsp() == nullptr) grid.sync();
;   volatile LAS unsigned* xst = (volatile LAS unsigned*)(smem + SMEM_MAIN);
;   if (t < 4) xst[t] = 0u;
;   __syncthreads();
;   const XcdBarrier xbar = xcd_barrier_post((unsigned*)(G_WS + OFF_BAR), xst);
_Z4mega6Params:
	s_mov_b64 s[70:71], s[0:1]
	s_mov_b32 s100, 0
	v_writelane_b32 v255, s100, 60
	v_writelane_b32 v255, s100, 61
	s_load_dwordx2 s[0:1], s[70:71], 0xd0
	s_load_dword s33, s[70:71], 0xd8
	v_and_b32_e32 v224, 0x3ff, v0
	v_writelane_b32 v252, s2, 0
	s_add_u32 s2, s70, 0xd0
	s_waitcnt lgkmcnt(0)
	v_writelane_b32 v252, s0, 1
	s_addc_u32 s3, s71, 0
	s_nop 0
	v_writelane_b32 v252, s1, 2
	s_mov_b32 s0, 25
	s_ashr_i32 s1, s0, 31
	s_lshl_b64 s[0:1], s[0:1], 3
	s_add_u32 s0, s70, s0
	s_addc_u32 s1, s71, s1
	s_load_dwordx2 s[4:5], s[0:1], 0x0
	s_movk_i32 s0, 0x3ff
	s_waitcnt lgkmcnt(0)
	s_cmp_lg_u64 s[4:5], 0
	s_cbranch_scc0 .LBB0_129
	v_cmp_gt_u32_e32 vcc, 4, v224
	s_and_saveexec_b64 s[0:1], vcc

; DI unsigned xb_add(unsigned* p, unsigned v) { return __hip_atomic_fetch_add(p, v, __ATOMIC_RELAXED, __HIP_MEMORY_SCOPE_AGENT); }
; DI void xcd_barrier(const XcdBarrier& b) {
;     ...
;     if (old + 1u == (gen + 1u) * nloc) {
;       __builtin_amdgcn_fence(__ATOMIC_RELEASE, "agent");
;       asm volatile("s_waitcnt vmcnt(0)" ::: "memory");
;       const unsigned og = xb_add(&bar[XB_TOP], 1u);
.LBB0_161:
	s_andn2_saveexec_b64 s[2:3], s[2:3]
	s_cbranch_execz .LBB0_181
	s_mov_b64 s[2:3], exec
	s_mov_b32 s100, 1
	v_writelane_b32 v255, s100, 61
	buffer_wbl2 sc1
	s_waitcnt lgkmcnt(0)
	s_waitcnt vmcnt(0)
	v_mbcnt_lo_u32_b32 v1, s2, 0
	v_mbcnt_hi_u32_b32 v1, s3, v1
	v_cmp_eq_u32_e32 vcc, 0, v1
	s_and_saveexec_b64 s[4:5], vcc
	s_cbranch_execz .LBB0_164
	s_bcnt1_i32_b64 s2, s[2:3]
	v_mov_b32_e32 v3, s2
	v_readlane_b32 s2, v253, 23
	v_mov_b32_e32 v2, 0
	v_readlane_b32 s3, v253, 24
	s_nop 4
	global_atomic_add v2, v2, v3, s[2:3] sc0

; DI unsigned xb_ld(unsigned* p) { return __hip_atomic_load(p, __ATOMIC_RELAXED, __HIP_MEMORY_SCOPE_AGENT); }
; DI unsigned xb_add(unsigned* p, unsigned v) { return __hip_atomic_fetch_add(p, v, __ATOMIC_RELAXED, __HIP_MEMORY_SCOPE_AGENT); }
; #define XB_SPIN(cond, bar) do { unsigned _sp = 0; while (cond) { __builtin_amdgcn_s_sleep(1); \
;     if ((++_sp & 255u) == 0u) { if (xb_ld(&(bar)[XB_TMO])) break; if (_sp > XB_SPIN_CAP) { atomicAdd(&(bar)[XB_TMO], 1u); break; } } } } while (0)
; DI void xcd_barrier(const XcdBarrier& b) {
;   asm volatile("s_waitcnt vmcnt(0)" ::: "memory");
;   __syncthreads();
;   if (threadIdx.x == 0) {
;     unsigned* bar = b.bar;
;     __builtin_amdgcn_s_waitcnt(0);
;     unsigned nloc = b.st[0], nx = b.st[1];
;     if (nloc == 0u) { xcd_barrier_complete(bar, b.x, nloc, nx); b.st[0] = nloc; b.st[1] = nx; }
;     const unsigned old = xb_add(&bar[XB_XSUB(b.x)], 1u);
;     const unsigned gen = old / nloc;
;     if (old + 1u == (gen + 1u) * nloc) {
;       __builtin_amdgcn_fence(__ATOMIC_RELEASE, "agent");
;       asm volatile("s_waitcnt vmcnt(0)" ::: "memory");
;       const unsigned og = xb_add(&bar[XB_TOP], 1u);
;       const unsigned tg = og / nx;
;       if (og + 1u == (tg + 1u) * nx) xb_add(&bar[XB_TOPGEN], 1u);
;       else XB_SPIN(xb_ld(&bar[XB_TOPGEN]) == tg, bar);
;       __builtin_amdgcn_fence(__ATOMIC_ACQUIRE, "agent");
.LBB0_490:
	s_waitcnt vmcnt(0)
	s_waitcnt lgkmcnt(0)
	s_barrier
	s_mov_b64 s[0:1], exec
	v_readlane_b32 s2, v252, 3
	v_readlane_b32 s3, v252, 4
	s_and_b64 s[2:3], s[0:1], s[2:3]
	s_mov_b64 exec, s[2:3]
	s_cbranch_execz .LBB0_542
	v_readlane_b32 s100, v255, 60
	v_readlane_b32 s5, v255, 61
	v_readlane_b32 s2, v253, 19
	v_readlane_b32 s3, v253, 20
	v_mov_b32_e32 v0, 1
	s_add_u32 s100, s100, 1
	s_waitcnt vmcnt(0) lgkmcnt(0)
	s_nop 4
	global_atomic_add v2, v0, s[2:3]
	buffer_inv sc1
	v_writelane_b32 v255, s100, 60
	s_add_u32 s101, s100, 1
	s_mov_b32 s100, 0
	s_cmp_eq_u32 s5, 0
	s_cbranch_scc1 .Lgs_fol_1
	v_mov_b32_e32 v0, 0x21000
	ds_read_b32 v1, v0
	s_waitcnt lgkmcnt(0)
	s_nop 0
	v_readfirstlane_b32 s4, v1
	s_nop 0
	s_mul_i32 s4, s4, s101
.Lgs_l1_1:
	global_load_dword v0, v2, s[2:3] sc1
	s_waitcnt vmcnt(0)
	v_readfirstlane_b32 s5, v0
	s_add_u32 s100, s100, 1
	s_cmp_ge_u32 s5, s4
	s_cbranch_scc1 .Lgs_l1d_1
	s_cmp_lt_u32 s100, 0x8000
	s_cbranch_scc0 .Lgs_l1d_1
	s_sleep 1
	s_branch .Lgs_l1_1
.Lgs_l1d_1:
	buffer_wbl2 sc1
	v_readlane_b32 s2, v253, 23
	v_readlane_b32 s3, v253, 24
	v_mov_b32_e32 v0, 0x21004
	ds_read_b32 v1, v0
	v_mov_b32_e32 v0, 1
	s_waitcnt vmcnt(0) lgkmcnt(0)
	v_readfirstlane_b32 s4, v1
	s_nop 4
	global_atomic_add v2, v0, s[2:3]
	s_mul_i32 s4, s4, s101
	s_mov_b32 s100, 0

; #define GSYNC() do { for (int _r = 0; _r < REP_SYNC; ++_r) xcd_barrier(xbar); } while (0)
; DI unsigned xb_ld(unsigned* p) { return __hip_atomic_load(p, __ATOMIC_RELAXED, __HIP_MEMORY_SCOPE_AGENT); }
; DI unsigned xb_add(unsigned* p, unsigned v) { return __hip_atomic_fetch_add(p, v, __ATOMIC_RELAXED, __HIP_MEMORY_SCOPE_AGENT); }
; #define XB_SPIN(cond, bar) do { unsigned _sp = 0; while (cond) { __builtin_amdgcn_s_sleep(1); \
;     if ((++_sp & 255u) == 0u) { if (xb_ld(&(bar)[XB_TMO])) break; if (_sp > XB_SPIN_CAP) { atomicAdd(&(bar)[XB_TMO], 1u); break; } } } } while (0)
; #define G_SSCQ ((float*)(wsp() + OFF_SSCQ))
; #define G_SSCKV ((float*)(wsp() + OFF_SSCKV))
; DI void xcd_barrier(const XcdBarrier& b) {
;     ...
;       if (og + 1u == (tg + 1u) * nx) xb_add(&bar[XB_TOPGEN], 1u);
;       else XB_SPIN(xb_ld(&bar[XB_TOPGEN]) == tg, bar);
;       __builtin_amdgcn_fence(__ATOMIC_ACQUIRE, "agent");
;       xb_add(&bar[XB_XGEN(b.x)], 1u);
;       asm volatile("s_waitcnt vmcnt(0)" ::: "memory");
;     } else {
;       XB_SPIN(xb_ld(&bar[XB_XGEN(b.x)]) == gen, bar);
;       __builtin_amdgcn_fence(__ATOMIC_ACQUIRE, "agent");
;       asm volatile("s_waitcnt vmcnt(0)" ::: "memory");
;     }
;   }
;   __syncthreads();
; __global__ void __launch_bounds__(512, 2) mega(Params p) {
;     ...
;     GSYNC();
;     if (odd) {
;       const int total = 3 * 64 + 8 * 64;
;       for (int rp = 0; rp < REP_P1; ++rp)
;       for (int item = bid; item < total; item += nb) {
;         if (item < 192) {
;           const int nt = item >> 6, mt = item & 63;
;           e.ss = G_SSCQ; e.nss = 4; e.inv_n = 1.f / 256.f; e.out = G_QC; e.ldo = 768;
;           gemm_tile<EPI_UQ, 256, false>(G_ZB, ZLD, wb + W_UQ, 256, mt * 256, nt * 256, e);
;         } else {
;           const int it = item - 192;
;           const int nt = it >> 6, mt = it & 63;
;           e.ss = G_SSCKV; e.nss = 2; e.inv_n = 1.f / 128.f; e.out = G_KVC; e.ldo = 1024;
;           gemm_tile<EPI_PLAIN, 128, false>(G_ZB + 256, ZLD, wb + W_UKV, 128, mt * 256, nt * 128, e);
.Lgs_l2d_1:
	v_readlane_b32 s2, v253, 21
	v_readlane_b32 s3, v253, 22
	v_mov_b32_e32 v0, 1
	s_nop 4
	global_atomic_add v2, v0, s[2:3]
	s_branch .Lgs_end_1
.Lgs_fol_1:
	v_readlane_b32 s2, v253, 21
	v_readlane_b32 s3, v253, 22
	s_nop 4
.Lgs_f1_1:
	global_load_dword v0, v2, s[2:3] sc1
	s_waitcnt vmcnt(0)
	v_readfirstlane_b32 s5, v0
	s_add_u32 s100, s100, 1
	s_cmp_ge_u32 s5, s101
	s_cbranch_scc1 .Lgs_end_1
	s_cmp_lt_u32 s100, 0x8000
	s_cbranch_scc0 .Lgs_end_1
	s_sleep 1
	s_branch .Lgs_f1_1
.Lgs_end_1:
.LBB0_542:
	s_or_b64 exec, exec, s[0:1]
	s_and_b64 vcc, exec, s[38:39]
	s_waitcnt lgkmcnt(0)
	s_barrier
	s_cbranch_vccz .LBB0_631
	v_readlane_b32 s0, v253, 34
	v_readlane_b32 s1, v253, 35
	s_andn2_b64 vcc, exec, s[0:1]
	s_cbranch_vccnz .LBB0_578
	v_readlane_b32 s0, v254, 44
	s_add_u32 s4, s0, 0x460000
	v_readlane_b32 s1, v254, 45
	s_addc_u32 s5, s1, 0
	s_add_u32 s7, s0, 0x400000
	s_addc_u32 s20, s1, 0
	v_readlane_b32 s21, v254, 17
	v_readlane_b32 s24, v254, 21
	v_readlane_b32 s25, v254, 19
	v_readlane_b32 s33, v252, 0
	s_branch .LBB0_547

; DI unsigned xb_ld(unsigned* p) { return __hip_atomic_load(p, __ATOMIC_RELAXED, __HIP_MEMORY_SCOPE_AGENT); }
; DI unsigned xb_add(unsigned* p, unsigned v) { return __hip_atomic_fetch_add(p, v, __ATOMIC_RELAXED, __HIP_MEMORY_SCOPE_AGENT); }
; #define XB_SPIN(cond, bar) do { unsigned _sp = 0; while (cond) { __builtin_amdgcn_s_sleep(1); \
;     if ((++_sp & 255u) == 0u) { if (xb_ld(&(bar)[XB_TMO])) break; if (_sp > XB_SPIN_CAP) { atomicAdd(&(bar)[XB_TMO], 1u); break; } } } } while (0)
; DI void xcd_barrier(const XcdBarrier& b) {
;   asm volatile("s_waitcnt vmcnt(0)" ::: "memory");
;   __syncthreads();
;   if (threadIdx.x == 0) {
;     unsigned* bar = b.bar;
;     __builtin_amdgcn_s_waitcnt(0);
;     unsigned nloc = b.st[0], nx = b.st[1];
;     if (nloc == 0u) { xcd_barrier_complete(bar, b.x, nloc, nx); b.st[0] = nloc; b.st[1] = nx; }
;     const unsigned old = xb_add(&bar[XB_XSUB(b.x)], 1u);
;     const unsigned gen = old / nloc;
;     if (old + 1u == (gen + 1u) * nloc) {
;       __builtin_amdgcn_fence(__ATOMIC_RELEASE, "agent");
;       asm volatile("s_waitcnt vmcnt(0)" ::: "memory");
;       const unsigned og = xb_add(&bar[XB_TOP], 1u);
;       const unsigned tg = og / nx;
;       if (og + 1u == (tg + 1u) * nx) xb_add(&bar[XB_TOPGEN], 1u);
;       else XB_SPIN(xb_ld(&bar[XB_TOPGEN]) == tg, bar);
;       __builtin_amdgcn_fence(__ATOMIC_ACQUIRE, "agent");
.LBB0_578:
	s_waitcnt vmcnt(0)
	s_barrier
	s_mov_b64 s[0:1], exec
	v_readlane_b32 s2, v252, 3
	v_readlane_b32 s3, v252, 4
	s_and_b64 s[2:3], s[0:1], s[2:3]
	s_mov_b64 exec, s[2:3]
	s_cbranch_execz .LBB0_630
	v_readlane_b32 s100, v255, 60
	v_readlane_b32 s5, v255, 61
	v_readlane_b32 s2, v253, 19
	v_readlane_b32 s3, v253, 20
	v_mov_b32_e32 v0, 1
	s_add_u32 s100, s100, 1
	s_waitcnt vmcnt(0) lgkmcnt(0)
	s_nop 4
	global_atomic_add v2, v0, s[2:3]
	buffer_inv sc1
	v_writelane_b32 v255, s100, 60
	s_add_u32 s101, s100, 1
	s_mov_b32 s100, 0
	s_cmp_eq_u32 s5, 0
	s_cbranch_scc1 .Lgs_fol_2
	v_mov_b32_e32 v0, 0x21000
	ds_read_b32 v1, v0
	s_waitcnt lgkmcnt(0)
	s_nop 0
	v_readfirstlane_b32 s4, v1
	s_nop 0
	s_mul_i32 s4, s4, s101

; DI void xcd_barrier(const XcdBarrier& b) {
;     ...
;   __syncthreads();
.Lgs_end_2:
.LBB0_630:
	s_or_b64 exec, exec, s[0:1]
	s_waitcnt lgkmcnt(0)
	s_barrier

; #define GSYNC() do { for (int _r = 0; _r < REP_SYNC; ++_r) xcd_barrier(xbar); } while (0)
; #define G_XF (outp())
; #define G_SS ((float*)(wsp() + OFF_SS))
; DI void xcd_barrier(const XcdBarrier& b) {
;     ...
;   __syncthreads();
; __global__ void __launch_bounds__(512, 2) mega(Params p) {
;     ...
;     GSYNC();
;     for (int item = bid; item < 4 * 64; item += nb) {
;       const int nt = item >> 6, mt = item & 63;
;       e.ss = nullptr; e.xf = G_XF; e.xb = G_XB; e.ss_out = G_SS;
;       gemm_tile<EPI_RESID, 256, false>(G_OB, DM, wb + W_OUT, DM, mt * 256, nt * 256, e);
.Lgs_end_3:
.LBB0_902:
	s_or_b64 exec, exec, s[0:1]
	v_readlane_b32 s0, v253, 38
	v_readlane_b32 s1, v253, 39
	s_and_b64 vcc, exec, s[0:1]
	s_waitcnt lgkmcnt(0)
	s_barrier
	s_cbranch_vccz .LBB0_945
	v_readlane_b32 s0, v254, 44
	s_add_u32 s14, s0, 0x4a0000
	v_readlane_b32 s0, v254, 45
	s_addc_u32 s15, s0, 0
	v_readlane_b32 s0, v254, 42
	v_readlane_b32 s2, v254, 48
	v_readlane_b32 s1, v254, 43
	s_add_u32 s4, s0, s2
	s_addc_u32 s5, s1, 0
	v_readlane_b32 s20, v254, 19
	v_readlane_b32 s21, v254, 17
	v_readlane_b32 s24, v252, 0
	s_branch .LBB0_905

; #define GSYNC() do { for (int _r = 0; _r < REP_SYNC; ++_r) xcd_barrier(xbar); } while (0)
; #define G_SS ((float*)(wsp() + OFF_SS))
; #define G_SSMEM ((float*)(wsp() + OFF_SSMEM))
; __global__ void __launch_bounds__(512, 2) mega(Params p) {
;     ...
;     GSYNC();
;     for (int rp = 0; rp < REP_P4; ++rp)
;     for (int item = bid; item < 2 * 64 + 4 * 8; item += nb) {
;       if (item < 128) {
;         const int nt = item >> 6, mt = item & 63;
;         e.ss = G_SS; e.nss = 16; e.inv_n = 1.f / 1024.f; e.out = G_XQ; e.ldo = 512;
;         gemm_tile<EPI_PLAIN, 256, true>(G_XB, DM, wb + W_XQ, DM, mt * 256, nt * 256, e);
;       } else {
;         const int it = item - 128;
;         const int nt = it >> 3, mt = it & 7;
;         e.ss = G_SSMEM; e.nss = 1; e.inv_n = 1.f / 1024.f; e.out = G_MEMKV; e.ldo = 1024;
;         gemm_tile<EPI_PLAIN, 256, false>(G_MEMB, DM, wb + W_XKV, DM, mt * 256, nt * 256, e);
.Lgs_end_4:
.LBB0_997:
	s_or_b64 exec, exec, s[0:1]
	v_readlane_b32 s0, v253, 40
	v_readlane_b32 s1, v253, 41
	s_andn2_b64 vcc, exec, s[0:1]
	s_waitcnt lgkmcnt(0)
	s_barrier
	s_cbranch_vccnz .LBB0_1020
	v_readlane_b32 s0, v254, 44
	s_add_u32 s24, s0, 0x7a0000
	v_readlane_b32 s1, v254, 45
	s_addc_u32 s25, s1, 0
	s_add_u32 s30, s0, 0x6a0000
	s_addc_u32 s31, s1, 0
	v_readlane_b32 s0, v254, 42
	v_readlane_b32 s2, v254, 48
	v_readlane_b32 s1, v254, 43
	s_add_u32 s4, s0, s2
	s_addc_u32 s5, s1, 0
	v_readlane_b32 s33, v254, 17
	v_readlane_b32 s36, v254, 23
	v_readlane_b32 s37, v254, 19
	v_readlane_b32 s38, v252, 0
	s_branch .LBB0_1001

; #define GSYNC() do { for (int _r = 0; _r < REP_SYNC; ++_r) xcd_barrier(xbar); } while (0)
; __global__ void __launch_bounds__(512, 2) mega(Params p) {
;     ...
;     GSYNC();
;     for (int rp = 0; rp < REP_P4; ++rp)
;     for (int item = bid; item < 256; item += nb) {
;       const int pl = item & 7, rest = item >> 3;
;       const int qt = rest & 7, pg = rest >> 3;
;       const int pair = pg * 8 + pl;
;       const int b = pair >> 2, hd = pair & 3;
;       AttArgs a{};
;       a.q = G_XQ + (size_t)b * SEQ * 512 + hd * 128; a.ldq = 512;
;       a.k = G_MEMKV + (size_t)b * 256 * 1024 + hd * 128; a.ldk = 1024;
;       a.v = G_MEMKV + (size_t)b * 256 * 1024 + 512 + hd * 128; a.ldv = 1024;
;       a.o = G_XO + (size_t)b * SEQ * 512 + hd * 128; a.ldo = 512;
;       a.scale = 0.08838834764831845f;
;       attn_item<128, 128, 0, 1>(a, qt * 256, 0, 4);
.Lgs_end_5:
.LBB0_1072:
	s_or_b64 exec, exec, s[0:1]
	v_readlane_b32 s0, v253, 38
	v_readlane_b32 s1, v253, 39
	s_andn2_b64 vcc, exec, s[0:1]
	v_readlane_b32 s14, v252, 0
	s_waitcnt lgkmcnt(0)
	s_barrier
	s_cbranch_vccz .LBB0_1077

; #define GSYNC() do { for (int _r = 0; _r < REP_SYNC; ++_r) xcd_barrier(xbar); } while (0)
; __global__ void __launch_bounds__(512, 2) mega(Params p) {
;     ...
;     GSYNC();
;     for (int item = bid; item < 4 * 64; item += nb) {
.Lgs_end_6:
	s_branch .LBB0_1146

; #define MFMA32(a, b, c) __builtin_amdgcn_mfma_f32_32x32x16_bf16((a), (b), (c), 0, 0, 0)
; DI int crow(int i, int h) { return (i & 3) + 8 * (i >> 2) + 4 * h; }
; DI float fexp2(float x) { return __builtin_amdgcn_exp2f(x); }
; template <int DK, int DV, int MODE, int QB, bool PACK = false>
; DI void attn_item(const AttArgs& a, int q0, int t_lo, int t_hi) {
;     ...
;     if (active) {
;       f32x16 s[QB][2];
; #pragma unroll
;       for (int qb = 0; qb < QB; ++qb)
; #pragma unroll
;         for (int kb = 0; kb < 2; ++kb) {
; #pragma unroll
;           for (int i = 0; i < 16; ++i) s[qb][kb][i] = 0.f;
;           const unsigned char* kp = Kb + (kb * 32 + r) * KST + h * 16;
; #pragma unroll
;           for (int st = 0; st < NKS; ++st) {
;             const bf16x8 kf = *(const bf16x8*)(kp + st * 32);
;             s[qb][kb] = MFMA32(kf, qf[qb][st], s[qb][kb]);
;           }
;         }
; #pragma unroll
;       for (int qb = 0; qb < QB; ++qb) {
;         const int qidx = wq0 + qb * 32 + r;
;         float mloc = -1e30f;
; #pragma unroll
;         for (int kb = 0; kb < 2; ++kb)
; #pragma unroll
;           for (int i = 0; i < 16; ++i) {
;             float tt = s[qb][kb][i];
;             if constexpr (MODE == 1) {
;               const int kidx = tile * 64 + kb * 32 + crow(i, h);
;               const int d = kidx - qidx;
;               tt = (d <= 128 && d >= -128) ? tt : -1e30f;
;               s[qb][kb][i] = tt;
;             }
;             if constexpr (MODE == 2) {
;               const int kc = kb * 32 + crow(i, h);
;               const bool ok = (kc >= c0[qb]) && (kc < c0[qb] + 16);
;               const int bi = ok ? ((tile - rq + 7) * 31 + kc - cq[qb] + 15) : 0;
;               tt = ok ? fmaf(tt, scale, rpbs[bi]) : -1e30f;
;               s[qb][kb][i] = tt;
;             }
;             mloc = fmaxf(mloc, tt);
;           }
;         mloc = fmaxf(mloc, __shfl_xor(mloc, 32));
;         if (__any((mloc - m[qb]) * cexp > 8.f)) {
;           const float mnew = fmaxf(m[qb], mloc);
;           const float alpha = fexp2((m[qb] - mnew) * cexp);
;           m[qb] = mnew;
;           lsum[qb] *= alpha;
; #pragma unroll
;           for (int d = 0; d < NDB; ++d)
; #pragma unroll
;             for (int i = 0; i < 16; ++i) o[qb][d][i] *= alpha;
;         }
.LBB0_1095:
	v_add_u32_e32 v1, v162, v167
	ds_read_b128 v[4:7], v1 offset:34816
	ds_read_b128 v[8:11], v1 offset:34848
	s_mov_b32 s2, 0xf149f2ca
	s_waitcnt lgkmcnt(1)
	v_mfma_f32_32x32x16_bf16 v[80:95], v[4:7], v[140:143], 0
	ds_read_b128 v[4:7], v1 offset:34880
	s_waitcnt lgkmcnt(1)
	v_mfma_f32_32x32x16_bf16 v[80:95], v[8:11], v[136:139], v[80:95]
	s_waitcnt lgkmcnt(0)
	v_mfma_f32_32x32x16_bf16 v[80:95], v[4:7], v[132:135], v[80:95]
	ds_read_b128 v[4:7], v1 offset:34912
	s_waitcnt lgkmcnt(0)
	v_mfma_f32_32x32x16_bf16 v[80:95], v[4:7], v[128:131], v[80:95]
	ds_read_b128 v[4:7], v1 offset:34944
	s_waitcnt lgkmcnt(0)
	v_mfma_f32_32x32x16_bf16 v[80:95], v[4:7], v[124:127], v[80:95]
	ds_read_b128 v[4:7], v1 offset:34976
	s_waitcnt lgkmcnt(0)
	v_mfma_f32_32x32x16_bf16 v[80:95], v[4:7], v[120:123], v[80:95]
	ds_read_b128 v[4:7], v1 offset:35008
	s_waitcnt lgkmcnt(0)
	v_mfma_f32_32x32x16_bf16 v[80:95], v[4:7], v[116:119], v[80:95]
	ds_read_b128 v[4:7], v1 offset:35040
	s_waitcnt lgkmcnt(0)
	v_mfma_f32_32x32x16_bf16 v[80:95], v[4:7], v[112:115], v[80:95]
	ds_read_b128 v[4:7], v1 offset:43520
	s_waitcnt lgkmcnt(0)
	v_mfma_f32_32x32x16_bf16 v[96:111], v[4:7], v[140:143], 0
	ds_read_b128 v[4:7], v1 offset:43552
	s_waitcnt lgkmcnt(0)
	v_mfma_f32_32x32x16_bf16 v[96:111], v[4:7], v[136:139], v[96:111]
	ds_read_b128 v[4:7], v1 offset:43584
	s_waitcnt lgkmcnt(0)
	v_mfma_f32_32x32x16_bf16 v[96:111], v[4:7], v[132:135], v[96:111]
	ds_read_b128 v[4:7], v1 offset:43616
	s_waitcnt lgkmcnt(0)
	v_mfma_f32_32x32x16_bf16 v[96:111], v[4:7], v[128:131], v[96:111]
	ds_read_b128 v[4:7], v1 offset:43648
	s_waitcnt lgkmcnt(0)
	v_mfma_f32_32x32x16_bf16 v[96:111], v[4:7], v[124:127], v[96:111]
	ds_read_b128 v[4:7], v1 offset:43680
	s_waitcnt lgkmcnt(0)
	v_mfma_f32_32x32x16_bf16 v[96:111], v[4:7], v[120:123], v[96:111]
	ds_read_b128 v[4:7], v1 offset:43712
	s_waitcnt lgkmcnt(0)
	v_mfma_f32_32x32x16_bf16 v[96:111], v[4:7], v[116:119], v[96:111]
	ds_read_b128 v[4:7], v1 offset:43744
	v_max3_f32 v1, v80, s2, v81
	v_max3_f32 v1, v1, v82, v83
	v_max3_f32 v1, v1, v84, v85
	v_max3_f32 v1, v1, v86, v87
	v_max3_f32 v1, v1, v88, v89
	v_max3_f32 v1, v1, v90, v91
	s_waitcnt lgkmcnt(0)
	v_mfma_f32_32x32x16_bf16 v[96:111], v[4:7], v[112:115], v[96:111]
	v_max3_f32 v1, v1, v92, v93
	v_max3_f32 v1, v1, v94, v95
	s_mov_b32 s2, 0x41000000
	s_nop 8
	v_max3_f32 v1, v1, v96, v97
	v_max3_f32 v1, v1, v98, v99
	v_max3_f32 v1, v1, v100, v101
	v_max3_f32 v1, v1, v102, v103
	v_max3_f32 v1, v1, v104, v105
	v_max3_f32 v1, v1, v106, v107
	v_max3_f32 v1, v1, v108, v109
	v_max3_f32 v1, v1, v110, v111
	ds_bpermute_b32 v4, v3, v1
	s_waitcnt lgkmcnt(0)
	v_max_f32_e32 v4, v4, v4
	v_max_f32_e32 v1, v1, v4
	v_sub_f32_e32 v4, v1, v168
	v_mul_f32_e32 v4, 0x3e0293ee, v4
	v_cmp_lt_f32_e32 vcc, s2, v4
	s_cbranch_vccz .LBB0_1076
	v_max_f32_e32 v0, v1, v1
	v_max_f32_e32 v1, v168, v168
	v_max_f32_e32 v1, v1, v0
	v_sub_f32_e32 v0, v168, v1
	v_mul_f32_e32 v0, 0x3e0293ee, v0
	v_exp_f32_e32 v0, v0
	s_nop 0
	v_pk_mul_f32 v[78:79], v[78:79], v[0:1] op_sel_hi:[1,0]
	v_pk_mul_f32 v[76:77], v[76:77], v[0:1] op_sel_hi:[1,0]
	v_pk_mul_f32 v[74:75], v[74:75], v[0:1] op_sel_hi:[1,0]
	v_pk_mul_f32 v[72:73], v[72:73], v[0:1] op_sel_hi:[1,0]
	v_pk_mul_f32 v[70:71], v[70:71], v[0:1] op_sel_hi:[1,0]
	v_pk_mul_f32 v[68:69], v[68:69], v[0:1] op_sel_hi:[1,0]
	v_pk_mul_f32 v[66:67], v[66:67], v[0:1] op_sel_hi:[1,0]
	v_pk_mul_f32 v[64:65], v[64:65], v[0:1] op_sel_hi:[1,0]
	v_pk_mul_f32 v[62:63], v[62:63], v[0:1] op_sel_hi:[1,0]
	v_pk_mul_f32 v[60:61], v[60:61], v[0:1] op_sel_hi:[1,0]
	v_pk_mul_f32 v[58:59], v[58:59], v[0:1] op_sel_hi:[1,0]
	v_pk_mul_f32 v[56:57], v[56:57], v[0:1] op_sel_hi:[1,0]
	v_pk_mul_f32 v[54:55], v[54:55], v[0:1] op_sel_hi:[1,0]
	v_pk_mul_f32 v[52:53], v[52:53], v[0:1] op_sel_hi:[1,0]
	v_pk_mul_f32 v[50:51], v[50:51], v[0:1] op_sel_hi:[1,0]
	v_pk_mul_f32 v[48:49], v[48:49], v[0:1] op_sel_hi:[1,0]
	v_pk_mul_f32 v[46:47], v[46:47], v[0:1] op_sel_hi:[1,0]
	v_pk_mul_f32 v[44:45], v[44:45], v[0:1] op_sel_hi:[1,0]
	v_pk_mul_f32 v[42:43], v[42:43], v[0:1] op_sel_hi:[1,0]
	v_pk_mul_f32 v[40:41], v[40:41], v[0:1] op_sel_hi:[1,0]
	v_pk_mul_f32 v[38:39], v[38:39], v[0:1] op_sel_hi:[1,0]
	v_pk_mul_f32 v[36:37], v[36:37], v[0:1] op_sel_hi:[1,0]
	v_pk_mul_f32 v[34:35], v[34:35], v[0:1] op_sel_hi:[1,0]
	v_pk_mul_f32 v[32:33], v[32:33], v[0:1] op_sel_hi:[1,0]
	v_pk_mul_f32 v[30:31], v[30:31], v[0:1] op_sel_hi:[1,0]
	v_pk_mul_f32 v[28:29], v[28:29], v[0:1] op_sel_hi:[1,0]
	v_pk_mul_f32 v[26:27], v[26:27], v[0:1] op_sel_hi:[1,0]
	v_pk_mul_f32 v[24:25], v[24:25], v[0:1] op_sel_hi:[1,0]
	v_pk_mul_f32 v[22:23], v[22:23], v[0:1] op_sel_hi:[1,0]
	v_pk_mul_f32 v[20:21], v[20:21], v[0:1] op_sel_hi:[1,0]
	v_pk_mul_f32 v[18:19], v[18:19], v[0:1] op_sel_hi:[1,0]
	v_pk_mul_f32 v[16:17], v[16:17], v[0:1] op_sel_hi:[1,0]
	v_mul_f32_e32 v164, v164, v0
	v_mul_f32_e32 v0, 0xbe0293ee, v1
	s_branch .LBB0_1076
.LBB0_1146:
	s_or_b64 exec, exec, s[0:1]
	v_readlane_b32 s0, v253, 38
	v_readlane_b32 s1, v253, 39
	s_and_b64 vcc, exec, s[0:1]
	s_waitcnt lgkmcnt(0)
	s_barrier
	s_cbranch_vccz .LBB0_1189
	v_readlane_b32 s0, v254, 44
	s_add_u32 s14, s0, 0x9a0000
	v_readlane_b32 s0, v254, 45
	s_addc_u32 s15, s0, 0
	v_readlane_b32 s0, v254, 42
	v_readlane_b32 s2, v254, 48
	v_readlane_b32 s1, v254, 43
	s_add_u32 s4, s0, s2
	s_addc_u32 s5, s1, 0
	v_readlane_b32 s20, v254, 19
	v_readlane_b32 s21, v254, 17
	v_readlane_b32 s24, v252, 0
	s_branch .LBB0_1149

; #define GSYNC() do { for (int _r = 0; _r < REP_SYNC; ++_r) xcd_barrier(xbar); } while (0)
; #define G_SS ((float*)(wsp() + OFF_SS))
; __global__ void __launch_bounds__(512, 2) mega(Params p) {
;     ...
;     GSYNC();
;     bool pre7 = false;
;     for (int rp = 0; rp < REP_P7; ++rp)
;     for (int item = bid; item < 20 * 64 + 4 * 64; item += nb) {
;       e.ss = G_SS; e.nss = 16; e.inv_n = 1.f / 1024.f; e.out = G_ACT; e.ldo = 2816;
;       if (item < 1280) {
;         const int nt = item >> 6, mt = item & 63;
;         const int nxt = item + nb;
;         const bool chain = nxt < 1280;
;         gemm_tile256<EPI_GU, true>(G_XB, DM, wb + W_GU, DM, mt * 256, nt * 256, e, pre7, chain ? (nxt & 63) * 256 : -1, (nxt >> 6) * 256);
.Lgs_end_7:
.LBB0_1241:
	s_or_b64 exec, exec, s[0:1]
	v_readlane_b32 s0, v253, 42
	v_readlane_b32 s1, v253, 43
	s_andn2_b64 vcc, exec, s[0:1]
	s_waitcnt lgkmcnt(0)
	s_barrier
	s_cbranch_vccnz .LBB0_1267
	v_readlane_b32 s0, v254, 44
	s_add_u32 s4, s0, 0xaa0000
	v_readlane_b32 s0, v254, 45
	s_addc_u32 s5, s0, 0
	v_readlane_b32 s0, v254, 42
	v_readlane_b32 s2, v254, 48
	v_readlane_b32 s1, v254, 43
	s_add_u32 s6, s0, s2
	s_addc_u32 s7, s1, 0
	s_mov_b64 s[8:9], 0
	v_readlane_b32 s20, v254, 17
	v_readlane_b32 s21, v254, 21
	v_readlane_b32 s24, v254, 19
	v_readlane_b32 s25, v252, 0
	s_branch .LBB0_1245

; #define GSYNC() do { for (int _r = 0; _r < REP_SYNC; ++_r) xcd_barrier(xbar); } while (0)
; #define G_XF (outp())
; #define G_SS ((float*)(wsp() + OFF_SS))
; __global__ void __launch_bounds__(512, 2) mega(Params p) {
;     ...
;     GSYNC();
;     for (int item = bid; item < 4 * 64; item += nb) {
;       const int nt = item >> 6, mt = item & 63;
;       e.ss = nullptr; e.xf = G_XF; e.xb = G_XB; e.ss_out = G_SS;
;       gemm_tile<EPI_RESID, 256, false>(G_ACT, 2816, wb + W_DOWN, 2816, mt * 256, nt * 256, e);
.Lgs_end_8:
.LBB0_1319:
	s_or_b64 exec, exec, s[0:1]
	v_readlane_b32 s0, v253, 38
	v_readlane_b32 s1, v253, 39
	s_and_b64 vcc, exec, s[0:1]
	s_waitcnt lgkmcnt(0)
	s_barrier
	s_cbranch_vccz .LBB0_1362
	v_readlane_b32 s0, v254, 44
	s_add_u32 s14, s0, 0x15a0000
	v_readlane_b32 s0, v254, 45
	s_addc_u32 s15, s0, 0
	v_readlane_b32 s0, v254, 42
	v_readlane_b32 s2, v254, 48
	v_readlane_b32 s1, v254, 43
	s_add_u32 s4, s0, s2
	s_addc_u32 s5, s1, 0
	v_readlane_b32 s20, v254, 19
	v_readlane_b32 s21, v254, 17
	v_readlane_b32 s24, v252, 0
	s_branch .LBB0_1322

; DI unsigned xb_ld(unsigned* p) { return __hip_atomic_load(p, __ATOMIC_RELAXED, __HIP_MEMORY_SCOPE_AGENT); }
; DI unsigned xb_add(unsigned* p, unsigned v) { return __hip_atomic_fetch_add(p, v, __ATOMIC_RELAXED, __HIP_MEMORY_SCOPE_AGENT); }
; #define XB_SPIN(cond, bar) do { unsigned _sp = 0; while (cond) { __builtin_amdgcn_s_sleep(1); \
;     if ((++_sp & 255u) == 0u) { if (xb_ld(&(bar)[XB_TMO])) break; if (_sp > XB_SPIN_CAP) { atomicAdd(&(bar)[XB_TMO], 1u); break; } } } } while (0)
; DI void xcd_barrier(const XcdBarrier& b) {
;   asm volatile("s_waitcnt vmcnt(0)" ::: "memory");
;   __syncthreads();
;   if (threadIdx.x == 0) {
;     unsigned* bar = b.bar;
;     __builtin_amdgcn_s_waitcnt(0);
;     unsigned nloc = b.st[0], nx = b.st[1];
;     if (nloc == 0u) { xcd_barrier_complete(bar, b.x, nloc, nx); b.st[0] = nloc; b.st[1] = nx; }
;     const unsigned old = xb_add(&bar[XB_XSUB(b.x)], 1u);
;     const unsigned gen = old / nloc;
;     if (old + 1u == (gen + 1u) * nloc) {
;       __builtin_amdgcn_fence(__ATOMIC_RELEASE, "agent");
;       asm volatile("s_waitcnt vmcnt(0)" ::: "memory");
;       const unsigned og = xb_add(&bar[XB_TOP], 1u);
;       const unsigned tg = og / nx;
;       if (og + 1u == (tg + 1u) * nx) xb_add(&bar[XB_TOPGEN], 1u);
;       else XB_SPIN(xb_ld(&bar[XB_TOPGEN]) == tg, bar);
;       __builtin_amdgcn_fence(__ATOMIC_ACQUIRE, "agent");
.LBB0_1363:
	v_readlane_b32 s100, v255, 60
	v_readlane_b32 s5, v255, 61
	v_readlane_b32 s2, v253, 19
	v_readlane_b32 s3, v253, 20
	v_mov_b32_e32 v0, 1
	s_add_u32 s100, s100, 1
	s_waitcnt vmcnt(0) lgkmcnt(0)
	s_nop 4
	global_atomic_add v2, v0, s[2:3]
	buffer_inv sc1
	v_writelane_b32 v255, s100, 60
	s_add_u32 s101, s100, 1
	s_mov_b32 s100, 0
	s_cmp_eq_u32 s5, 0
	s_cbranch_scc1 .Lgs_fol_9
	v_mov_b32_e32 v0, 0x21000
	ds_read_b32 v1, v0
	s_waitcnt lgkmcnt(0)
	s_nop 0
	v_readfirstlane_b32 s4, v1
	s_nop 0
	s_mul_i32 s4, s4, s101

; #define GSYNC() do { for (int _r = 0; _r < REP_SYNC; ++_r) xcd_barrier(xbar); } while (0)
; DI unsigned xb_ld(unsigned* p) { return __hip_atomic_load(p, __ATOMIC_RELAXED, __HIP_MEMORY_SCOPE_AGENT); }
; DI unsigned xb_add(unsigned* p, unsigned v) { return __hip_atomic_fetch_add(p, v, __ATOMIC_RELAXED, __HIP_MEMORY_SCOPE_AGENT); }
; #define XB_SPIN(cond, bar) do { unsigned _sp = 0; while (cond) { __builtin_amdgcn_s_sleep(1); \
;     if ((++_sp & 255u) == 0u) { if (xb_ld(&(bar)[XB_TMO])) break; if (_sp > XB_SPIN_CAP) { atomicAdd(&(bar)[XB_TMO], 1u); break; } } } } while (0)
; DI void xcd_barrier(const XcdBarrier& b) {
;     ...
;       xb_add(&bar[XB_XGEN(b.x)], 1u);
;       asm volatile("s_waitcnt vmcnt(0)" ::: "memory");
;     } else {
;       XB_SPIN(xb_ld(&bar[XB_XGEN(b.x)]) == gen, bar);
;       __builtin_amdgcn_fence(__ATOMIC_ACQUIRE, "agent");
;       asm volatile("s_waitcnt vmcnt(0)" ::: "memory");
;     }
;   }
;   __syncthreads();
; __global__ void __launch_bounds__(512, 2) mega(Params p) {
;     ...
;     GSYNC();
;   }
.Lgs_end_9:
	s_mov_b64 s[4:5], 0
	s_getpc_b64 s[98:99]
.Lpost_getpc0:
	s_add_u32 s98, s98, (.LBB0_182-.Lpost_getpc0)&4294967295
	s_addc_u32 s99, s99, (.LBB0_182-.Lpost_getpc0)>>32
	s_setpc_b64 s[98:99]
	s_getpc_b64 s[98:99]
